# G4 thin product with four rotating register sets of 4-k-step load groups (36-48 loads always in flight) + norm_mod1 software pipelining
# baseline (speedup 1.0000x reference)
; #define MFMA16(a, b, c) __builtin_amdgcn_mfma_f32_16x16x32_bf16((a), (b), (c), 0, 0, 0)
; DI void phase_g4(const Params& p, const Sub& s, char* lds_all) {
;     ...
;     for (int rt = blockIdx.x; rt < 256; rt += gridDim.x) {
;       const int r0 = rt * 256 + wid * 32;
;       const bf16_t* a0p = A + (size_t)(r0 + fr) * D + fq * 8;
;       const bf16_t* a1p = a0p + (size_t)16 * D;
;       const bf16_t* bp = Bt + (size_t)(3072 + fr) * D + fq * 8;
;       f32x4 c0 = (f32x4){0.f, 0.f, 0.f, 0.f}, c1 = (f32x4){0.f, 0.f, 0.f, 0.f};
; #pragma unroll 8
;       for (int ks = 0; ks < 32; ++ks) {
;         const bf16x8 bb = *(const bf16x8*)(bp + ks * 32);
;         const bf16x8 x0 = *(const bf16x8*)(a0p + ks * 32), x1 = *(const bf16x8*)(a1p + ks * 32);
;         c0 = MFMA16(bb, x0, c0); c1 = MFMA16(bb, x1, c1);
.LBB0_1178:
	v_add_co_u32_e32 v216, vcc, 0xe00000, v16
	s_nop 0
	v_addc_co_u32_e32 v217, vcc, 0, v17, vcc
	v_add_co_u32_e32 v218, vcc, 0x1800000, v18
	s_nop 0
	v_addc_co_u32_e32 v219, vcc, 0, v19, vcc
	v_add_co_u32_e32 v220, vcc, 0x1808000, v18
	s_nop 0
	v_addc_co_u32_e32 v221, vcc, 0, v19, vcc
	global_load_dwordx4 v[22:25], v[216:217], off
	global_load_dwordx4 v[26:29], v[218:219], off
	global_load_dwordx4 v[30:33], v[220:221], off
	global_load_dwordx4 v[34:37], v[216:217], off offset:64
	global_load_dwordx4 v[38:41], v[218:219], off offset:64
	global_load_dwordx4 v[42:45], v[220:221], off offset:64
	global_load_dwordx4 v[46:49], v[216:217], off offset:128
	global_load_dwordx4 v[50:53], v[218:219], off offset:128
	global_load_dwordx4 v[54:57], v[220:221], off offset:128
	global_load_dwordx4 v[58:61], v[216:217], off offset:192
	global_load_dwordx4 v[62:65], v[218:219], off offset:192
	global_load_dwordx4 v[66:69], v[220:221], off offset:192
	global_load_dwordx4 v[70:73], v[216:217], off offset:256
	global_load_dwordx4 v[74:77], v[218:219], off offset:256
	global_load_dwordx4 v[78:81], v[220:221], off offset:256
	global_load_dwordx4 v[82:85], v[216:217], off offset:320
	global_load_dwordx4 v[86:89], v[218:219], off offset:320
	global_load_dwordx4 v[90:93], v[220:221], off offset:320
	global_load_dwordx4 v[94:97], v[216:217], off offset:384
	global_load_dwordx4 v[98:101], v[218:219], off offset:384
	global_load_dwordx4 v[102:105], v[220:221], off offset:384
	global_load_dwordx4 v[106:109], v[216:217], off offset:448
	global_load_dwordx4 v[110:113], v[218:219], off offset:448
	global_load_dwordx4 v[114:117], v[220:221], off offset:448
	global_load_dwordx4 v[118:121], v[216:217], off offset:512
	global_load_dwordx4 v[122:125], v[218:219], off offset:512
	global_load_dwordx4 v[126:129], v[220:221], off offset:512
	global_load_dwordx4 v[130:133], v[216:217], off offset:576
	global_load_dwordx4 v[134:137], v[218:219], off offset:576
	global_load_dwordx4 v[138:141], v[220:221], off offset:576
	global_load_dwordx4 v[142:145], v[216:217], off offset:640
	global_load_dwordx4 v[146:149], v[218:219], off offset:640
	global_load_dwordx4 v[150:153], v[220:221], off offset:640
	global_load_dwordx4 v[154:157], v[216:217], off offset:704
	global_load_dwordx4 v[158:161], v[218:219], off offset:704
	global_load_dwordx4 v[162:165], v[220:221], off offset:704
	global_load_dwordx4 v[166:169], v[216:217], off offset:768
	global_load_dwordx4 v[170:173], v[218:219], off offset:768
	global_load_dwordx4 v[174:177], v[220:221], off offset:768
	global_load_dwordx4 v[178:181], v[216:217], off offset:832
	global_load_dwordx4 v[184:187], v[218:219], off offset:832
	global_load_dwordx4 v[188:191], v[220:221], off offset:832
	global_load_dwordx4 v[192:195], v[216:217], off offset:896
	global_load_dwordx4 v[196:199], v[218:219], off offset:896
	global_load_dwordx4 v[200:203], v[220:221], off offset:896
	global_load_dwordx4 v[204:207], v[216:217], off offset:960
	global_load_dwordx4 v[208:211], v[218:219], off offset:960
	global_load_dwordx4 v[212:215], v[220:221], off offset:960
	s_waitcnt vmcnt(36)
	v_mfma_f32_16x16x32_bf16 v[0:3], v[22:25], v[26:29], v[0:3]
	v_mfma_f32_16x16x32_bf16 v[4:7], v[22:25], v[30:33], v[4:7]
	v_mfma_f32_16x16x32_bf16 v[0:3], v[34:37], v[38:41], v[0:3]
	v_mfma_f32_16x16x32_bf16 v[4:7], v[34:37], v[42:45], v[4:7]
	v_mfma_f32_16x16x32_bf16 v[0:3], v[46:49], v[50:53], v[0:3]
	v_mfma_f32_16x16x32_bf16 v[4:7], v[46:49], v[54:57], v[4:7]
	v_mfma_f32_16x16x32_bf16 v[0:3], v[58:61], v[62:65], v[0:3]
	v_mfma_f32_16x16x32_bf16 v[4:7], v[58:61], v[66:69], v[4:7]
	global_load_dwordx4 v[22:25], v[216:217], off offset:1024
	global_load_dwordx4 v[26:29], v[218:219], off offset:1024
	global_load_dwordx4 v[30:33], v[220:221], off offset:1024
	global_load_dwordx4 v[34:37], v[216:217], off offset:1088
	global_load_dwordx4 v[38:41], v[218:219], off offset:1088
	global_load_dwordx4 v[42:45], v[220:221], off offset:1088
	global_load_dwordx4 v[46:49], v[216:217], off offset:1152
	global_load_dwordx4 v[50:53], v[218:219], off offset:1152
	global_load_dwordx4 v[54:57], v[220:221], off offset:1152
	global_load_dwordx4 v[58:61], v[216:217], off offset:1216
	global_load_dwordx4 v[62:65], v[218:219], off offset:1216
	global_load_dwordx4 v[66:69], v[220:221], off offset:1216
	s_waitcnt vmcnt(36)
	v_mfma_f32_16x16x32_bf16 v[0:3], v[70:73], v[74:77], v[0:3]
	v_mfma_f32_16x16x32_bf16 v[4:7], v[70:73], v[78:81], v[4:7]
	v_mfma_f32_16x16x32_bf16 v[0:3], v[82:85], v[86:89], v[0:3]
	v_mfma_f32_16x16x32_bf16 v[4:7], v[82:85], v[90:93], v[4:7]
	v_mfma_f32_16x16x32_bf16 v[0:3], v[94:97], v[98:101], v[0:3]
	v_mfma_f32_16x16x32_bf16 v[4:7], v[94:97], v[102:105], v[4:7]
	v_mfma_f32_16x16x32_bf16 v[0:3], v[106:109], v[110:113], v[0:3]
	v_mfma_f32_16x16x32_bf16 v[4:7], v[106:109], v[114:117], v[4:7]
	global_load_dwordx4 v[70:73], v[216:217], off offset:1280
	global_load_dwordx4 v[74:77], v[218:219], off offset:1280
	global_load_dwordx4 v[78:81], v[220:221], off offset:1280
	global_load_dwordx4 v[82:85], v[216:217], off offset:1344
	global_load_dwordx4 v[86:89], v[218:219], off offset:1344
	global_load_dwordx4 v[90:93], v[220:221], off offset:1344
	global_load_dwordx4 v[94:97], v[216:217], off offset:1408
	global_load_dwordx4 v[98:101], v[218:219], off offset:1408
	global_load_dwordx4 v[102:105], v[220:221], off offset:1408
	global_load_dwordx4 v[106:109], v[216:217], off offset:1472
	global_load_dwordx4 v[110:113], v[218:219], off offset:1472
	global_load_dwordx4 v[114:117], v[220:221], off offset:1472
	s_waitcnt vmcnt(36)
; #define MFMA16(a, b, c) __builtin_amdgcn_mfma_f32_16x16x32_bf16((a), (b), (c), 0, 0, 0)
; DI void phase_g4(const Params& p, const Sub& s, char* lds_all) {
;     ...
;       for (int ks = 0; ks < 32; ++ks) {
;         const bf16x8 bb = *(const bf16x8*)(bp + ks * 32);
;         const bf16x8 x0 = *(const bf16x8*)(a0p + ks * 32), x1 = *(const bf16x8*)(a1p + ks * 32);
;         c0 = MFMA16(bb, x0, c0); c1 = MFMA16(bb, x1, c1);
;       }
;       *(f32x4*)(ba + (size_t)(r0 + fr) * 16 + 4 * fq) = c0;
;       *(f32x4*)(ba + (size_t)(r0 + 16 + fr) * 16 + 4 * fq) = c1;
;     }
	v_mfma_f32_16x16x32_bf16 v[0:3], v[118:121], v[122:125], v[0:3]
	v_mfma_f32_16x16x32_bf16 v[4:7], v[118:121], v[126:129], v[4:7]
	v_mfma_f32_16x16x32_bf16 v[0:3], v[130:133], v[134:137], v[0:3]
	v_mfma_f32_16x16x32_bf16 v[4:7], v[130:133], v[138:141], v[4:7]
	v_mfma_f32_16x16x32_bf16 v[0:3], v[142:145], v[146:149], v[0:3]
	v_mfma_f32_16x16x32_bf16 v[4:7], v[142:145], v[150:153], v[4:7]
	v_mfma_f32_16x16x32_bf16 v[0:3], v[154:157], v[158:161], v[0:3]
	v_mfma_f32_16x16x32_bf16 v[4:7], v[154:157], v[162:165], v[4:7]
	global_load_dwordx4 v[118:121], v[216:217], off offset:1536
	global_load_dwordx4 v[122:125], v[218:219], off offset:1536
	global_load_dwordx4 v[126:129], v[220:221], off offset:1536
	global_load_dwordx4 v[130:133], v[216:217], off offset:1600
	global_load_dwordx4 v[134:137], v[218:219], off offset:1600
	global_load_dwordx4 v[138:141], v[220:221], off offset:1600
	global_load_dwordx4 v[142:145], v[216:217], off offset:1664
	global_load_dwordx4 v[146:149], v[218:219], off offset:1664
	global_load_dwordx4 v[150:153], v[220:221], off offset:1664
	global_load_dwordx4 v[154:157], v[216:217], off offset:1728
	global_load_dwordx4 v[158:161], v[218:219], off offset:1728
	global_load_dwordx4 v[162:165], v[220:221], off offset:1728
	s_waitcnt vmcnt(36)
	v_mfma_f32_16x16x32_bf16 v[0:3], v[166:169], v[170:173], v[0:3]
	v_mfma_f32_16x16x32_bf16 v[4:7], v[166:169], v[174:177], v[4:7]
	v_mfma_f32_16x16x32_bf16 v[0:3], v[178:181], v[184:187], v[0:3]
	v_mfma_f32_16x16x32_bf16 v[4:7], v[178:181], v[188:191], v[4:7]
	v_mfma_f32_16x16x32_bf16 v[0:3], v[192:195], v[196:199], v[0:3]
	v_mfma_f32_16x16x32_bf16 v[4:7], v[192:195], v[200:203], v[4:7]
	v_mfma_f32_16x16x32_bf16 v[0:3], v[204:207], v[208:211], v[0:3]
	v_mfma_f32_16x16x32_bf16 v[4:7], v[204:207], v[212:215], v[4:7]
	global_load_dwordx4 v[166:169], v[216:217], off offset:1792
	global_load_dwordx4 v[170:173], v[218:219], off offset:1792
	global_load_dwordx4 v[174:177], v[220:221], off offset:1792
	global_load_dwordx4 v[178:181], v[216:217], off offset:1856
	global_load_dwordx4 v[184:187], v[218:219], off offset:1856
	global_load_dwordx4 v[188:191], v[220:221], off offset:1856
	global_load_dwordx4 v[192:195], v[216:217], off offset:1920
	global_load_dwordx4 v[196:199], v[218:219], off offset:1920
	global_load_dwordx4 v[200:203], v[220:221], off offset:1920
	global_load_dwordx4 v[204:207], v[216:217], off offset:1984
	global_load_dwordx4 v[208:211], v[218:219], off offset:1984
	global_load_dwordx4 v[212:215], v[220:221], off offset:1984
	s_waitcnt vmcnt(36)
	v_mfma_f32_16x16x32_bf16 v[0:3], v[22:25], v[26:29], v[0:3]
	v_mfma_f32_16x16x32_bf16 v[4:7], v[22:25], v[30:33], v[4:7]
	v_mfma_f32_16x16x32_bf16 v[0:3], v[34:37], v[38:41], v[0:3]
	v_mfma_f32_16x16x32_bf16 v[4:7], v[34:37], v[42:45], v[4:7]
	v_mfma_f32_16x16x32_bf16 v[0:3], v[46:49], v[50:53], v[0:3]
	v_mfma_f32_16x16x32_bf16 v[4:7], v[46:49], v[54:57], v[4:7]
	v_mfma_f32_16x16x32_bf16 v[0:3], v[58:61], v[62:65], v[0:3]
	v_mfma_f32_16x16x32_bf16 v[4:7], v[58:61], v[66:69], v[4:7]
	s_waitcnt vmcnt(24)
	v_mfma_f32_16x16x32_bf16 v[0:3], v[70:73], v[74:77], v[0:3]
	v_mfma_f32_16x16x32_bf16 v[4:7], v[70:73], v[78:81], v[4:7]
	v_mfma_f32_16x16x32_bf16 v[0:3], v[82:85], v[86:89], v[0:3]
	v_mfma_f32_16x16x32_bf16 v[4:7], v[82:85], v[90:93], v[4:7]
	v_mfma_f32_16x16x32_bf16 v[0:3], v[94:97], v[98:101], v[0:3]
	v_mfma_f32_16x16x32_bf16 v[4:7], v[94:97], v[102:105], v[4:7]
	v_mfma_f32_16x16x32_bf16 v[0:3], v[106:109], v[110:113], v[0:3]
	v_mfma_f32_16x16x32_bf16 v[4:7], v[106:109], v[114:117], v[4:7]
	s_waitcnt vmcnt(12)
	v_mfma_f32_16x16x32_bf16 v[0:3], v[118:121], v[122:125], v[0:3]
	v_mfma_f32_16x16x32_bf16 v[4:7], v[118:121], v[126:129], v[4:7]
	v_mfma_f32_16x16x32_bf16 v[0:3], v[130:133], v[134:137], v[0:3]
	v_mfma_f32_16x16x32_bf16 v[4:7], v[130:133], v[138:141], v[4:7]
	v_mfma_f32_16x16x32_bf16 v[0:3], v[142:145], v[146:149], v[0:3]
	v_mfma_f32_16x16x32_bf16 v[4:7], v[142:145], v[150:153], v[4:7]
	v_mfma_f32_16x16x32_bf16 v[0:3], v[154:157], v[158:161], v[0:3]
	v_mfma_f32_16x16x32_bf16 v[4:7], v[154:157], v[162:165], v[4:7]
	s_waitcnt vmcnt(0)
	v_mfma_f32_16x16x32_bf16 v[0:3], v[166:169], v[170:173], v[0:3]
	v_mfma_f32_16x16x32_bf16 v[4:7], v[166:169], v[174:177], v[4:7]
	v_mfma_f32_16x16x32_bf16 v[0:3], v[178:181], v[184:187], v[0:3]
	v_mfma_f32_16x16x32_bf16 v[4:7], v[178:181], v[188:191], v[4:7]
	v_mfma_f32_16x16x32_bf16 v[0:3], v[192:195], v[196:199], v[0:3]
	v_mfma_f32_16x16x32_bf16 v[4:7], v[192:195], v[200:203], v[4:7]
	v_mfma_f32_16x16x32_bf16 v[0:3], v[204:207], v[208:211], v[0:3]
	v_mfma_f32_16x16x32_bf16 v[4:7], v[204:207], v[212:215], v[4:7]
	v_lshl_add_u32 v18, s3, 8, v20
	v_ashrrev_i32_e32 v19, 31, v18
	v_lshlrev_b64 v[22:23], 6, v[18:19]
	v_lshl_add_u64 v[22:23], v[10:11], 0, v[22:23]
	s_nop 0
	global_store_dwordx4 v[22:23], v[0:3], off
	v_readlane_b32 s0, v251, 1
	s_add_i32 s3, s3, s0
	v_or_b32_e32 v0, 16, v18
	v_ashrrev_i32_e32 v1, 31, v0
	v_lshlrev_b64 v[0:1], 6, v[0:1]
	v_lshl_add_u64 v[0:1], v[10:11], 0, v[0:1]
	s_cmpk_gt_i32 s3, 0xff
	v_add_u32_e32 v14, s2, v14
	global_store_dwordx4 v[0:1], v[4:7], off
	v_readlane_b32 s1, v251, 2
	s_cbranch_scc0 .LBB0_1177
